# static priority raise (s_setprio 1 at phase entry) for waves 4-7 in the HGRN2 / GDN / NA mixer phases
# speedup vs baseline: 1.0002x; 1.0002x over previous
; template <int L> __device__ __forceinline__ void layer_body(Frame& F, const Args& args, unsigned char* const wsg, const int lo, const int hi, const XcdBarrier& bar) {
;     ...
;             if (m == 0) phase_hg2(F, j, !last);
;             else if (m == 1) phase_gdn2(F, !last);
;             else phase_na2(F, !last);
.LBB0_246:
	s_cmp_lt_u32 s33, 4
	s_cbranch_scc1 .Lpr_3
	s_setprio 1
